# mLSTM: conv/load thread mapping so raw q/k row loads cover 8 rows x 128B per instruction; H stores as 2x dwordx4; og loads issued before the prefetch loads
# baseline (speedup 1.0000x reference)
; DI void mlstm_seq(LAS unsigned char* lds, const bf16* P, const float* IFg, bf16* Hout, const float* conv_w, const float* conv_b, const float* mlg, int seq) {
;     ...
;     const int isk = (tid >> 8) & 1, cgp = (tid >> 5) & 7, rg = tid & 31;
;     const int chb = isk * 512 + hd * 64 + 8 * cgp, lch = isk * 64 + 8 * cgp;
.LBB0_331:
	s_or_b64 exec, exec, s[0:1]
	v_bfe_u32 v66, v58, 8, 1
	v_lshlrev_b32_e32 v97, 24, v66
	v_lshl_or_b32 v0, s19, 21, v97
	v_readlane_b32 s0, v255, 0
	v_and_b32_e32 v65, 7, v58
	v_add_u32_e32 v0, 0x9000000, v0
	s_ashr_i32 s16, s0, 3
	v_lshlrev_b32_e32 v95, 3, v65
	v_and_b32_e32 v0, 0xb800000, v0
	s_and_b32 s0, s8, 0xc0
	v_or_b32_e32 v4, s0, v95
	v_lshlrev_b32_e32 v0, 1, v0
	v_bfe_u32 v59, v58, 3, 5
	s_ashr_i32 s17, s16, 31
	v_lshl_add_u64 v[2:3], s[86:87], 0, v[0:1]
	v_lshlrev_b32_e32 v0, 1, v4
	s_lshl_b64 s[2:3], s[16:17], 11
	v_lshlrev_b32_e32 v72, 1, v59
	v_lshl_add_u64 v[80:81], v[2:3], 0, v[0:1]
	v_cmp_lt_u32_e32 vcc, 1, v59
	v_mov_b32_e32 v22, 0
	v_mov_b32_e32 v26, 0
	v_mov_b32_e32 v27, 0
	v_mov_b32_e32 v28, 0
	v_mov_b32_e32 v29, 0
	s_waitcnt lgkmcnt(0)
	s_barrier
	s_and_saveexec_b64 s[0:1], vcc
	s_cbranch_execz .LBB0_333
	v_add_u32_e32 v0, -3, v72
	v_lshl_add_u64 v[2:3], s[2:3], 0, v[0:1]
	v_lshlrev_b64 v[2:3], 9, v[2:3]
	v_lshl_add_u64 v[2:3], v[80:81], 0, v[2:3]
	global_load_dwordx4 v[26:29], v[2:3], off

; #define LAS __attribute__((address_space(3)))
; #define MFMA32(a, b, c) __builtin_amdgcn_mfma_f32_32x32x16_bf16((a), (b), (c), 0, 0, 0)
; DI size_t pidx(size_t row, int col) { return (size_t)(col >> 8) * ((size_t)TH * 256) + row * 256 + (size_t)(col & 255); }
; DI void mlstm_seq(LAS unsigned char* lds, const bf16* P, const float* IFg, bf16* Hout, const float* conv_w, const float* conv_b, const float* mlg, int seq) {
;     ...
;         const int t = 32 * th + r32; const size_t row = rowb + 64 * c + t;
;         v2u og[4];
; #pragma unroll
;         for (int rq = 0; rq < 4; ++rq) og[rq] = *(const v2u*)(P + pidx(row, 6656 + hd * 128 + 32 * dvs + 8 * rq + 4 * hh));
;         const float Mt = gate[64 + t], it = gate[128 + t], et = gate[192 + t], dec = gate[320];
;         bf16x8 qf[4];
; #pragma unroll
;         for (int kk = 0; kk < 4; ++kk) qf[kk] = *(const LAS bf16x8*)(Qt + t * 144 + 32 * kk + 16 * hh);
;         f32x16 sacc[2];
; #pragma unroll
;         for (int st = 0; st < 2; ++st) {
; #pragma unroll
;             for (int i = 0; i < 16; ++i) sacc[st][i] = 0.f;
;             if (st <= th) {
; #pragma unroll
;                 for (int kk = 0; kk < 4; ++kk) { const bf16x8 a = *(const LAS bf16x8*)(Kt + (32 * st + r32) * 144 + 32 * kk + 16 * hh); sacc[st] = MFMA32(a, qf[kk], sacc[st]); } }
;         }
;         float rowsum = 0.f; bf16x8 Wf[4];
; #pragma unroll
;         for (int st = 0; st < 2; ++st) {
;             if (st <= th) {
; #pragma unroll
;             for (int rq = 0; rq < 4; ++rq) { const f32x4 d4 = *(const LAS f32x4*)(gate + 32 * st + 8 * rq + 4 * hh);
; #pragma unroll
;                 for (int i = 0; i < 4; ++i) { const int s = 32 * st + 8 * rq + 4 * hh + i; const float e = __builtin_amdgcn_exp2f(d4[i] - Mt); const float w = (st < th || s <= t) ? sacc[st][4 * rq + i] * e : 0.f; rowsum += w; sacc[st][4 * rq + i] = w; } } }
.LBB0_356:
	s_and_b32 s14, s21, 7
	s_lshl_b32 s2, s14, 23
	s_add_i32 s3, s2, 0x16000000
	s_add_i32 s2, s2, 0x1a000000
	s_ashr_i32 s27, s18, 6
	s_and_b32 s13, s2, 0x1f000000
	s_and_b32 s2, s27, 3
	v_writelane_b32 v255, s21, 1
	s_and_b32 s21, s3, 0x1f000000
	s_ashr_i32 s23, s18, 8
	s_lshl_b32 s3, s2, 6
	s_lshl_b32 s22, s14, 2
	s_and_b32 s9, s20, 3
	s_lshl_b32 s8, s14, 8
	s_lshl_b32 s12, s23, 5
	s_lshl_b32 s10, s2, 5
	s_add_i32 s11, 0, 0x11800
	s_add_i32 s15, s3, 0
	s_lshl_b32 s2, s2, 8
	s_lshl_b32 s26, s27, 3
	s_and_b32 s19, s18, 0x3fffffc0
	s_cmp_eq_u32 s27, 5
	v_writelane_b32 v255, s20, 2
	s_cselect_b64 s[86:87], -1, 0
	s_add_i32 s20, 0, 0x12a00
	s_cmp_gt_i32 s23, -1
	v_lshrrev_b32_e32 v8, 5, v94
	s_cselect_b64 s[68:69], -1, 0
	s_cmp_gt_i32 s23, 0
	v_and_b32_e32 v2, 31, v94
	v_or_b32_e32 v2, s12, v2
	v_lshlrev_b32_e32 v9, 2, v8
	s_cselect_b64 s[74:75], -1, 0
	s_cmpk_lt_u32 s18, 0x100
	v_writelane_b32 v255, s2, 3
	s_cselect_b64 s[2:3], -1, 0
	v_cmp_gt_i32_e32 vcc, v9, v2
	s_and_b64 s[24:25], s[2:3], vcc
	v_writelane_b32 v255, s24, 4
	v_cmp_ge_i32_e32 vcc, v9, v2
	v_or_b32_e32 v0, 2, v9
	v_writelane_b32 v255, s25, 5
	s_and_b64 s[24:25], s[2:3], vcc
	v_writelane_b32 v255, s24, 6
	v_cmp_gt_i32_e32 vcc, v0, v2
	v_or_b32_e32 v0, 3, v9
	v_writelane_b32 v255, s25, 7
	s_and_b64 s[24:25], s[2:3], vcc
	v_cmp_gt_i32_e32 vcc, v0, v2
	v_or_b32_e32 v0, 8, v9
	s_and_b64 s[34:35], s[2:3], vcc
	v_cmp_gt_i32_e32 vcc, v0, v2
	v_or_b32_e32 v0, 9, v9
	s_and_b64 s[76:77], s[2:3], vcc
	v_cmp_gt_i32_e32 vcc, v0, v2
	v_or_b32_e32 v0, 10, v9
	s_and_b64 s[78:79], s[2:3], vcc
	v_cmp_gt_i32_e32 vcc, v0, v2
	v_or_b32_e32 v0, 11, v9
	s_and_b64 s[36:37], s[2:3], vcc
	v_cmp_gt_i32_e32 vcc, v0, v2
	v_or_b32_e32 v0, 16, v9
	s_and_b64 s[46:47], s[2:3], vcc
	v_cmp_gt_i32_e32 vcc, v0, v2
	v_or_b32_e32 v0, 17, v9
	s_and_b64 s[50:51], s[2:3], vcc
	v_cmp_gt_i32_e32 vcc, v0, v2
	v_or_b32_e32 v0, 18, v9
	s_and_b64 s[48:49], s[2:3], vcc
	v_cmp_gt_i32_e32 vcc, v0, v2
	v_or_b32_e32 v0, 19, v9
	s_and_b64 s[44:45], s[2:3], vcc
	v_cmp_gt_i32_e32 vcc, v0, v2
	v_or_b32_e32 v0, 24, v9
	s_and_b64 s[94:95], s[2:3], vcc
	v_cmp_gt_i32_e32 vcc, v0, v2
	v_or_b32_e32 v0, 25, v9
	s_and_b64 s[38:39], s[2:3], vcc
	v_cmp_gt_i32_e32 vcc, v0, v2
	v_or_b32_e32 v0, 26, v9
	s_and_b64 s[92:93], s[2:3], vcc
	v_cmp_gt_i32_e32 vcc, v0, v2
	v_or_b32_e32 v0, 27, v9
	s_and_b64 s[96:97], s[2:3], vcc
	v_cmp_gt_i32_e32 vcc, v0, v2
	s_and_b64 s[2:3], s[2:3], vcc
	v_writelane_b32 v255, s24, 8
	s_cmp_eq_u32 s23, 1
	v_or_b32_e32 v10, 32, v9
	v_writelane_b32 v255, s25, 9
	s_cselect_b64 s[24:25], -1, 0
	v_cmp_gt_i32_e32 vcc, v10, v2
	v_or_b32_e32 v0, 33, v9
	s_and_b64 s[66:67], s[24:25], vcc
	v_cmp_gt_i32_e32 vcc, v0, v2
	v_or_b32_e32 v0, 34, v9
	s_and_b64 s[80:81], s[24:25], vcc
	v_cmp_gt_i32_e32 vcc, v0, v2
	v_or_b32_e32 v0, 35, v9
	s_and_b64 s[64:65], s[24:25], vcc
	v_cmp_gt_i32_e32 vcc, v0, v2
	v_or_b32_e32 v0, 40, v9
	s_and_b64 s[82:83], s[24:25], vcc
	v_cmp_gt_i32_e32 vcc, v0, v2
	v_or_b32_e32 v0, 41, v9
	s_and_b64 s[40:41], s[24:25], vcc
	v_cmp_gt_i32_e32 vcc, v0, v2
	v_or_b32_e32 v0, 42, v9
	s_and_b64 s[42:43], s[24:25], vcc
	v_cmp_gt_i32_e32 vcc, v0, v2
	v_or_b32_e32 v0, 43, v9
	s_and_b64 s[52:53], s[24:25], vcc
	v_cmp_gt_i32_e32 vcc, v0, v2
	v_or_b32_e32 v0, 48, v9
	s_and_b64 s[54:55], s[24:25], vcc
	v_cmp_gt_i32_e32 vcc, v0, v2
	v_or_b32_e32 v0, 49, v9
	s_and_b64 s[56:57], s[24:25], vcc
	v_cmp_gt_i32_e32 vcc, v0, v2
	v_or_b32_e32 v0, 50, v9
	s_and_b64 s[58:59], s[24:25], vcc
	v_cmp_gt_i32_e32 vcc, v0, v2
	v_or_b32_e32 v0, 51, v9
	s_and_b64 s[60:61], s[24:25], vcc
	v_cmp_gt_i32_e32 vcc, v0, v2
	v_or_b32_e32 v0, 56, v9
	s_and_b64 s[62:63], s[24:25], vcc
	v_cmp_gt_i32_e32 vcc, v0, v2
	v_or_b32_e32 v0, 57, v9
	s_and_b64 s[70:71], s[24:25], vcc
	v_cmp_gt_i32_e32 vcc, v0, v2
	v_or_b32_e32 v0, 58, v9
	s_and_b64 s[90:91], s[24:25], vcc
	v_cmp_gt_i32_e32 vcc, v0, v2
	v_or_b32_e32 v0, 59, v9
	s_lshl_b32 s18, s27, 5
	s_and_b64 s[28:29], s[24:25], vcc
	v_cmp_gt_i32_e32 vcc, v0, v2
	s_add_i32 s33, s11, s18
	s_and_b64 s[30:31], s[24:25], vcc
	s_or_b32 s88, s26, 2
	s_add_i32 s26, s33, 16
	s_add_i32 s18, 0, 0x13500
	s_lshl_b64 s[24:25], s[16:17], 17
	v_readlane_b32 vcc_lo, v254, 60
	v_readlane_b32 vcc_hi, v254, 61
	s_add_u32 s23, vcc_lo, s24
	s_addc_u32 s24, vcc_hi, s25
	s_add_u32 s22, s22, s23
	s_addc_u32 s23, 0, s24
	v_lshlrev_b32_e32 v0, 6, v94
	v_lshl_add_u64 v[128:129], s[22:23], 0, v[0:1]
	s_lshl_b64 s[22:23], s[16:17], 20
	s_add_u32 s21, s21, s22
	s_addc_u32 s25, 0, s23
	s_add_u32 s24, s21, 0xb010000
	s_addc_u32 s25, s25, 0
	v_lshl_add_u32 v0, s14, 21, v97
	v_lshlrev_b64 v[4:5], 9, v[62:63]
	v_lshl_add_u32 v0, v0, 1, v197
; DI void mlstm_seq(LAS unsigned char* lds, const bf16* P, const float* IFg, bf16* Hout, const float* conv_w, const float* conv_b, const float* mlg, int seq) {
;     ...
;         const int t = 32 * th + r32; const size_t row = rowb + 64 * c + t;
;         v2u og[4];
; #pragma unroll
;         for (int rq = 0; rq < 4; ++rq) og[rq] = *(const v2u*)(P + pidx(row, 6656 + hd * 128 + 32 * dvs + 8 * rq + 4 * hh));
;         const float Mt = gate[64 + t], it = gate[128 + t], et = gate[192 + t], dec = gate[320];
;         bf16x8 qf[4];
; #pragma unroll
;         for (int kk = 0; kk < 4; ++kk) qf[kk] = *(const LAS bf16x8*)(Qt + t * 144 + 32 * kk + 16 * hh);
;         f32x16 sacc[2];
; #pragma unroll
;         for (int st = 0; st < 2; ++st) {
; #pragma unroll
;             for (int i = 0; i < 16; ++i) sacc[st][i] = 0.f;
;             if (st <= th) {
; #pragma unroll
;                 for (int kk = 0; kk < 4; ++kk) { const bf16x8 a = *(const LAS bf16x8*)(Kt + (32 * st + r32) * 144 + 32 * kk + 16 * hh); sacc[st] = MFMA32(a, qf[kk], sacc[st]); } }
;         }
;         float rowsum = 0.f; bf16x8 Wf[4];
; #pragma unroll
;         for (int st = 0; st < 2; ++st) {
;             if (st <= th) {
; #pragma unroll
;             for (int rq = 0; rq < 4; ++rq) { const f32x4 d4 = *(const LAS f32x4*)(gate + 32 * st + 8 * rq + 4 * hh);
; #pragma unroll
;                 for (int i = 0; i < 4; ++i) { const int s = 32 * st + 8 * rq + 4 * hh + i; const float e = __builtin_amdgcn_exp2f(d4[i] - Mt); const float w = (st < th || s <= t) ? sacc[st][4 * rq + i] * e : 0.f; rowsum += w; sacc[st][4 * rq + i] = w; } } }
;             Wf[2 * st] = pack8(sacc[st][0], sacc[st][1], sacc[st][2], sacc[st][3], sacc[st][4], sacc[st][5], sacc[st][6], sacc[st][7]);
;             Wf[2 * st + 1] = pack8(sacc[st][8], sacc[st][9], sacc[st][10], sacc[st][11], sacc[st][12], sacc[st][13], sacc[st][14], sacc[st][15]);
;         }
;         float qn = 0.f;
; #pragma unroll
;         for (int kk = 0; kk < 4; ++kk) { const f32x4 n0 = *(const LAS f32x4*)(nvec + 16 * kk + 8 * hh), n1 = *(const LAS f32x4*)(nvec + 16 * kk + 8 * hh + 4); const v4u q = __builtin_bit_cast(v4u, qf[kk]);
;             qn += lo_f(q.x) * n0[0] + hi_f(q.x) * n0[1] + lo_f(q.y) * n0[2] + hi_f(q.y) * n0[3] + lo_f(q.z) * n1[0] + hi_f(q.z) * n1[1] + lo_f(q.w) * n1[2] + hi_f(q.w) * n1[3]; }
;         qn += __shfl_xor(qn, 32); rowsum += __shfl_xor(rowsum, 32);
	s_add_u32 s13, s13, s22
	v_lshl_add_u64 v[130:131], s[24:25], 0, v[4:5]
	v_lshlrev_b64 v[4:5], 9, v[60:61]
	v_and_b32_e32 v0, 0x1f000000, v0
	s_addc_u32 s14, 0, s23
	v_lshl_add_u64 v[132:133], s[24:25], 0, v[4:5]
	v_lshl_add_u64 v[4:5], v[0:1], 0, s[22:23]
	s_add_u32 s22, s13, 0xb000020
	s_addc_u32 s23, s14, 0
	v_ashrrev_i32_e32 v3, 31, v2
	s_lshl_b64 s[16:17], s[16:17], 22
	v_lshlrev_b64 v[6:7], 9, v[2:3]
	s_add_u32 s16, s16, 0x37200020
	v_lshl_add_u64 v[134:135], s[22:23], 0, v[6:7]
	s_addc_u32 s17, s17, 0
	v_lshlrev_b64 v[6:7], 11, v[2:3]
	v_and_b32_e32 v0, 3, v58
	v_bfe_u32 v3, v58, 4, 1
	v_lshl_add_u64 v[136:137], s[16:17], 0, v[6:7]
	v_lshlrev_b32_e32 v6, 5, v3
	v_lshlrev_b32_e32 v7, 3, v0
	v_lshlrev_b32_e32 v3, 4, v3
	v_lshlrev_b32_e32 v0, 2, v0
	v_or3_b32 v0, v3, v0, s12
	v_lshlrev_b32_e32 v3, 2, v94
	v_readlane_b32 s12, v253, 57
	v_add_u32_e32 v186, s20, v3
	v_add_u32_e32 v203, s11, v3
	v_add_u32_e32 v184, s12, v3
	v_or_b32_e32 v3, s10, v9
	v_lshlrev_b32_e32 v208, 1, v3
	v_add3_u32 v6, s15, v6, v7
	v_lshlrev_b32_e32 v7, 2, v2
	v_or3_b32 v136, v136, s8, v208
	s_movk_i32 s8, 0x90
	v_add_u32_e32 v11, 0x100, v7
	v_add_u32_e32 v12, 0x200, v7
	v_add_u32_e32 v13, 0x300, v7
	v_mul_lo_u32 v20, v2, s8
	v_readlane_b32 s8, v253, 56
	v_lshlrev_b32_e32 v17, 1, v95
	v_add_u32_e32 v138, 0, v20
	v_add_u32_e32 v209, s8, v7
	v_add_u32_e32 v211, s8, v11
	v_add_u32_e32 v212, s8, v12
	v_add_u32_e32 v213, s8, v13
	s_movk_i32 s8, 0xb0
	v_lshl_add_u32 v204, v3, 2, s18
	v_or_b32_e32 v14, 8, v3
	v_or_b32_e32 v15, 16, v3
	v_or_b32_e32 v16, 24, v3
	v_lshl_or_b32 v17, s9, 7, v17
	v_bfe_u32 v3, v58, 2, 2
	v_mad_u64_u32 v[140:141], s[8:9], v2, s8, v[138:139]
	v_lshlrev_b32_e32 v201, 4, v8
	v_lshl_or_b32 v8, v8, 3, v3
	s_movk_i32 s8, 0x140
	v_mad_u32_u24 v141, v8, s8, v6
	v_readlane_b32 s8, v253, 58
	v_readlane_b32 s12, v254, 62
	v_readlane_b32 s13, v254, 63
	v_add_u32_e32 v215, s8, v201
	v_readlane_b32 s8, v253, 59
	v_cndmask_b32_e64 v18, 0, 1, s[12:13]
	v_lshlrev_b32_e32 v18, 7, v18
	v_add_u32_e32 v216, s8, v201
	v_readlane_b32 s8, v253, 60
	v_or_b32_e32 v19, s10, v18
	v_or_b32_e32 v18, v18, v98
	v_add_u32_e32 v217, s8, v201
	v_readlane_b32 s8, v253, 61
	v_lshlrev_b32_e32 v18, 1, v18
	v_or_b32_e32 v130, v130, v18
	v_add_u32_e32 v218, s8, v201
	v_readlane_b32 s8, v253, 62
	v_or_b32_e32 v132, v132, v18
	v_lshlrev_b32_e32 v18, 10, v59
	v_add_u32_e32 v219, s8, v201
	v_readlane_b32 s8, v253, 63
	v_or3_b32 v4, v4, v18, v17
	v_add_u32_e32 v187, s11, v11
	v_add_u32_e32 v220, s8, v201
	v_readlane_b32 s8, v254, 0
	v_and_b32_e32 v7, 32, v58
	v_or_b32_e32 v11, v9, v3
	v_add_u32_e32 v221, s8, v201
	v_readlane_b32 s8, v254, 1
	v_or_b32_e32 v3, v10, v3
	v_add_u32_e32 v199, s11, v12
	v_add_u32_e32 v222, s8, v201
	s_mov_b64 s[8:9], 0xb00fe00
	v_lshl_add_u64 v[142:143], v[4:5], 0, s[8:9]
	v_or_b32_e32 v4, v19, v9
	v_add_u32_e32 v200, s11, v13
	v_lshl_add_u32 v205, v14, 2, s18
	v_lshl_add_u32 v206, v15, 2, s18
	v_lshl_add_u32 v207, v16, 2, s18
	v_add_u32_e32 v20, 0, v201
	v_lshl_add_u32 v0, v0, 1, 0
	v_and_b32_e32 v2, 31, v94
	v_mul_u32_u24_e32 v2, 0x90, v2
	v_mul_u32_u24_e32 v12, 0x140, v11
	v_mul_u32_u24_e32 v8, 0xc0, v11
	v_lshlrev_b32_e32 v11, 1, v14
	v_lshlrev_b32_e32 v13, 1, v15
	v_lshlrev_b32_e32 v14, 1, v16
	v_mul_u32_u24_e32 v15, 0x180, v59
	v_mul_u32_u24_e32 v16, 0xc0, v96
	v_mul_u32_u24_e32 v10, 0x140, v3
	v_mul_u32_u24_e32 v3, 0xc0, v3
	v_lshl_or_b32 v134, v4, 1, v134
	v_mov_b32_e32 v223, 0
	v_add_u32_e32 v4, 0, v7
	v_lshl_add_u32 v185, s19, 2, v184
	v_add_u32_e32 v202, s11, v201
	v_lshl_add_u32 v210, v94, 1, 0
	v_add_u32_e32 v214, 0xc800, v141
	s_mulk_i32 s27, 0x480
	s_mulk_i32 s88, 0x90
	v_add_u32_e32 v224, 0x12a00, v4
	v_add_u32_e32 v225, v6, v12
	v_add_u32_e32 v226, v6, v10
	v_add_u32_e32 v227, v0, v8
	v_add_u32_e32 v228, v0, v3
	v_add_u32_e32 v229, v140, v11
	v_add_u32_e32 v230, v140, v13
	v_add_u32_e32 v231, v140, v14
	v_add_u32_e32 v232, v99, v15
	v_add_u32_e32 v233, v99, v16
	v_add_u32_e32 v234, v20, v2
	v_mov_b32_e32 v16, 0
	v_mov_b32_e32 v17, v223
	v_mov_b32_e32 v18, v223
	v_mov_b32_e32 v19, v223
	v_mov_b32_e32 v20, v223
	v_mov_b32_e32 v21, v223
	v_mov_b32_e32 v22, v223
	v_mov_b32_e32 v23, v223
	v_mov_b32_e32 v24, v223
	v_mov_b32_e32 v25, v223
	v_mov_b32_e32 v26, v223
	v_mov_b32_e32 v27, v223
	v_mov_b32_e32 v28, v223
	v_mov_b32_e32 v29, v223
	v_mov_b32_e32 v30, v223
	v_mov_b32_e32 v31, v223
	s_mov_b32 s89, 0
	v_cmp_gt_u32_e64 s[8:9], 32, v94
	v_cmp_eq_u32_e64 s[10:11], 0, v94
	v_cmp_gt_u32_e64 s[12:13], 2, v94
	v_cmp_gt_u32_e64 s[14:15], 4, v94
	v_cmp_gt_u32_e64 s[16:17], 8, v94
	v_cmp_gt_u32_e64 s[18:19], 16, v94
	s_waitcnt vmcnt(0)
	s_branch .LBB0_359

; DI size_t pidx(size_t row, int col) { return (size_t)(col >> 8) * ((size_t)TH * 256) + row * 256 + (size_t)(col & 255); }
; #define ML_PARK() do { _Pragma("unroll") for (int i = 0; i < 5; ++i) *(LAS v4u*)(slot + i * 8192) = qk[i]; *(LAS v4u*)(slot + 5 * 8192) = vv[0]; *(LAS v4u*)(slot + 6 * 8192) = vv[1]; pli2 = pli; plf2 = plf; } while (0)
; DI void mlstm_seq(LAS unsigned char* lds, const bf16* P, const float* IFg, bf16* Hout, const float* conv_w, const float* conv_b, const float* mlg, int seq) {
;     ...
;     for (int c = 0; c < 32; ++c) {
;         __syncthreads();
;         if (c < 31) ML_PARK();
;         if (c < 30) ML_LOAD(c + 2);
;         if (c < 31) ML_GCOMP();
;         const int t = 32 * th + r32; const size_t row = rowb + 64 * c + t;
;         v2u og[4];
; #pragma unroll
;         for (int rq = 0; rq < 4; ++rq) og[rq] = *(const v2u*)(P + pidx(row, 6656 + hd * 128 + 32 * dvs + 8 * rq + 4 * hh));
.LBB0_359:
	s_cmp_lg_u32 s89, 31
	s_cselect_b64 s[24:25], -1, 0
	s_cmp_eq_u32 s89, 31
	s_waitcnt lgkmcnt(0)
	s_barrier
	s_cbranch_scc1 .LBB0_361
	s_waitcnt vmcnt(2)
	v_mov_b32_e32 v125, v183
	v_mov_b32_e32 v139, v182
	ds_write_b128 v145, v[64:67]
	ds_write_b128 v145, v[68:71] offset:8192
	ds_write_b128 v145, v[72:75] offset:16384
	ds_write_b128 v145, v[76:79] offset:24576
	ds_write_b128 v145, v[80:83] offset:32768
	ds_write_b128 v145, v[84:87] offset:40960
	ds_write_b128 v145, v[88:91] offset:49152
.LBB0_361:
	v_readlane_b32 s20, v251, 8
	v_readlane_b32 s21, v251, 9
	s_nop 1
	v_lshl_add_u64 v[2:3], s[20:21], 0, v[134:135]
	global_load_dwordx2 v[152:153], v[2:3], off offset:-32
	global_load_dwordx2 v[150:151], v[2:3], off offset:-16
	global_load_dwordx2 v[148:149], v[2:3], off
	global_load_dwordx2 v[146:147], v[2:3], off offset:16
	s_cmp_gt_u32 s89, 29
	s_cbranch_scc1 .LBB0_364
	v_readlane_b32 s20, v251, 8
	v_readlane_b32 s21, v251, 9
	s_and_b64 vcc, exec, s[0:1]
	v_readlane_b32 s22, v251, 10
	v_lshl_add_u64 v[2:3], s[20:21], 0, v[142:143]
	global_load_dwordx4 v[64:67], v[2:3], off offset:-1024
	global_load_dwordx4 v[68:71], v[2:3], off offset:-512
	global_load_dwordx4 v[72:75], v[2:3], off
	global_load_dwordx4 v[76:79], v[2:3], off offset:512
	v_lshl_add_u64 v[4:5], s[20:21], 0, v[132:133]
	global_load_dwordx4 v[80:83], v[2:3], off offset:1024
	global_load_dwordx4 v[84:87], v[4:5], off
	v_lshl_add_u64 v[2:3], s[20:21], 0, v[130:131]
	global_load_dwordx4 v[88:91], v[2:3], off
	v_readlane_b32 s23, v251, 11
	s_cbranch_vccnz .LBB0_364
	v_readlane_b32 s20, v251, 8
	v_readlane_b32 s21, v251, 9
	v_readlane_b32 s22, v251, 10
	v_readlane_b32 s23, v251, 11
	v_lshl_add_u64 v[2:3], s[20:21], 0, v[128:129]
	v_add_co_u32_e32 v2, vcc, 0x2c02000, v2
	s_nop 1
	v_addc_co_u32_e32 v3, vcc, 0, v3, vcc
	global_load_dword v182, v[2:3], off
	global_load_dword v183, v[2:3], off offset:32

; #define LAS __attribute__((address_space(3)))
; #define MFMA32(a, b, c) __builtin_amdgcn_mfma_f32_32x32x16_bf16((a), (b), (c), 0, 0, 0)
; DI size_t pidx(size_t row, int col) { return (size_t)(col >> 8) * ((size_t)TH * 256) + row * 256 + (size_t)(col & 255); }
; DI void mlstm_seq(LAS unsigned char* lds, const bf16* P, const float* IFg, bf16* Hout, const float* conv_w, const float* conv_b, const float* mlg, int seq) {
;     ...
;         for (int rq = 0; rq < 4; ++rq) og[rq] = *(const v2u*)(P + pidx(row, 6656 + hd * 128 + 32 * dvs + 8 * rq + 4 * hh));
;         const float Mt = gate[64 + t], it = gate[128 + t], et = gate[192 + t], dec = gate[320];
;         bf16x8 qf[4];
; #pragma unroll
;         for (int kk = 0; kk < 4; ++kk) qf[kk] = *(const LAS bf16x8*)(Qt + t * 144 + 32 * kk + 16 * hh);
;         f32x16 sacc[2];
; #pragma unroll
;         for (int st = 0; st < 2; ++st) {
; #pragma unroll
;             for (int i = 0; i < 16; ++i) sacc[st][i] = 0.f;
;             if (st <= th) {
; #pragma unroll
;                 for (int kk = 0; kk < 4; ++kk) { const bf16x8 a = *(const LAS bf16x8*)(Kt + (32 * st + r32) * 144 + 32 * kk + 16 * hh); sacc[st] = MFMA32(a, qf[kk], sacc[st]); } }
.LBB0_366:
	v_readlane_b32 s20, v251, 8
	v_readlane_b32 s21, v251, 9
	s_andn2_b64 vcc, exec, s[68:69]
	v_readlane_b32 s22, v251, 10
	v_readlane_b32 s20, v253, 55
	ds_read_b32 v108, v187
	ds_read_b32 v235, v199
	ds_read_b32 v236, v200
	v_mov_b32_e32 v0, s20
	v_add_u32_e32 v2, v138, v201
	ds_read_b32 v144, v0
	ds_read_b128 v[104:107], v2
	ds_read_b128 v[100:103], v2 offset:32
	ds_read_b128 v[96:99], v2 offset:64
	ds_read_b128 v[92:95], v2 offset:96
	v_cndmask_b32_e64 v0, 0, 1, s[68:69]
	v_cmp_ne_u32_e64 s[20:21], 1, v0
	v_readlane_b32 s23, v251, 11
	s_cbranch_vccnz .LBB0_369
	ds_read_b128 v[2:5], v234 offset:9216
	s_waitcnt lgkmcnt(0)
	v_mfma_f32_32x32x16_bf16 v[48:63], v[2:5], v[104:107], 0
	ds_read_b128 v[2:5], v234 offset:9248
	s_waitcnt lgkmcnt(0)
	v_mfma_f32_32x32x16_bf16 v[48:63], v[2:5], v[100:103], v[48:63]
	ds_read_b128 v[2:5], v234 offset:9280
	s_waitcnt lgkmcnt(0)
	v_mfma_f32_32x32x16_bf16 v[48:63], v[2:5], v[96:99], v[48:63]
	ds_read_b128 v[2:5], v234 offset:9312
	s_waitcnt lgkmcnt(0)
	v_mfma_f32_32x32x16_bf16 v[48:63], v[2:5], v[92:95], v[48:63]
	v_cndmask_b32_e64 v0, 0, 1, s[74:75]
	v_cmp_ne_u32_e64 s[22:23], 1, v0
	s_andn2_b64 vcc, exec, s[74:75]
	s_cbranch_vccz .LBB0_370

; #define LAS __attribute__((address_space(3)))
; #define MFMA32(a, b, c) __builtin_amdgcn_mfma_f32_32x32x16_bf16((a), (b), (c), 0, 0, 0)
; DI float lo_f(unsigned u) { return __uint_as_float(u << 16); }
; DI float hi_f(unsigned u) { return __uint_as_float(u & 0xffff0000u); }
; DI float bf2f(unsigned short b) { return __uint_as_float((unsigned)b << 16); }
; DI void mlstm_seq(LAS unsigned char* lds, const bf16* P, const float* IFg, bf16* Hout, const float* conv_w, const float* conv_b, const float* mlg, int seq) {
;     ...
;         for (int i = 0; i < 16; ++i) Cst[i] *= dec;
; #pragma unroll
;         for (int k4 = 0; k4 < 4; ++k4) { const f32x4 wa = *(const LAS f32x4*)(gate + 256 + 16 * k4 + 4 * hh), wb = *(const LAS f32x4*)(gate + 256 + 16 * k4 + 8 + 4 * hh);
;             LAS unsigned char* p = Kt2 + (16 * k4 + 4 * hh + q4) * 192 + 2 * (32 * th + 16 * gg + 4 * p4); const v4u kq = __builtin_bit_cast(v4u, tr8(p, p + 8 * 192));
;             const bf16x8 kf2 = pack8(lo_f(kq.x) * wa[0], hi_f(kq.x) * wa[1], lo_f(kq.y) * wa[2], hi_f(kq.y) * wa[3], lo_f(kq.z) * wb[0], hi_f(kq.z) * wb[1], lo_f(kq.w) * wb[2], hi_f(kq.w) * wb[3]);
;             Cst = MFMA32(vf[k4], kf2, Cst); }
;         { float np = 0.f;
; #pragma unroll
;             for (int i = 0; i < 8; ++i) { const int s = 8 * wv + i; np += gate[256 + s] * bf2f(*(const LAS unsigned short*)(Kt + s * 144 + 2 * lane)); }
;             npart[wv * 64 + lane] = np; }
;         __syncthreads();
;         const float tot = ssq[t] + ssq[64 + t] + ssq[128 + t] + ssq[192 + t]; const float rstd = rsqrtf(tot * (1.0f / 128.0f) + 1e-6f);
; #pragma unroll
;         for (int rq = 0; rq < 4; ++rq) { const int dv = 32 * dvs + 8 * rq + 4 * hh; const f32x4 gl = *(const LAS f32x4*)(mlgl + dv);
;             const float o0 = hv[4 * rq] * rstd * gl[0] * lo_f(og[rq].x), o1 = hv[4 * rq + 1] * rstd * gl[1] * hi_f(og[rq].x), o2 = hv[4 * rq + 2] * rstd * gl[2] * lo_f(og[rq].y), o3 = hv[4 * rq + 3] * rstd * gl[3] * hi_f(og[rq].y);
.LBB0_383:
	s_or_b64 exec, exec, s[20:21]
	s_waitcnt lgkmcnt(0)
	ds_read_b128 v[2:5], v215
	ds_read_b128 v[6:9], v216
	ds_read_b64_tr_b16 v[10:11], v227 offset:18432
	ds_read_b64_tr_b16 v[12:13], v227 offset:19968
	v_pk_mul_f32 v[30:31], v[30:31], v[144:145] op_sel_hi:[1,0]
	v_pk_mul_f32 v[28:29], v[28:29], v[144:145] op_sel_hi:[1,0]
	v_pk_mul_f32 v[26:27], v[26:27], v[144:145] op_sel_hi:[1,0]
	s_waitcnt lgkmcnt(1)
	v_lshlrev_b32_e32 v32, 16, v10
	v_and_b32_e32 v10, 0xffff0000, v10
	v_mul_f32_e32 v3, v3, v10
	v_lshlrev_b32_e32 v10, 16, v11
	v_mul_f32_e32 v4, v4, v10
	v_and_b32_e32 v10, 0xffff0000, v11
	v_mul_f32_e32 v5, v5, v10
	s_waitcnt lgkmcnt(0)
	v_lshlrev_b32_e32 v10, 16, v12
	v_mul_f32_e32 v6, v6, v10
	v_and_b32_e32 v10, 0xffff0000, v12
	v_mul_f32_e32 v7, v7, v10
	v_lshlrev_b32_e32 v10, 16, v13
	v_mul_f32_e32 v8, v8, v10
	v_and_b32_e32 v10, 0xffff0000, v13
	v_mul_f32_e32 v2, v2, v32
	v_mul_f32_e32 v9, v9, v10
	v_cvt_pk_bf16_f32 v2, v2, v3
	v_cvt_pk_bf16_f32 v3, v4, v5
	v_cvt_pk_bf16_f32 v4, v6, v7
	v_cvt_pk_bf16_f32 v5, v8, v9
	ds_read_b128 v[6:9], v217
	ds_read_b128 v[10:13], v218
	ds_read_b64_tr_b16 v[32:33], v227 offset:21504
	ds_read_b64_tr_b16 v[34:35], v227 offset:23040
	v_pk_mul_f32 v[24:25], v[24:25], v[144:145] op_sel_hi:[1,0]
	v_pk_mul_f32 v[22:23], v[22:23], v[144:145] op_sel_hi:[1,0]
	v_pk_mul_f32 v[20:21], v[20:21], v[144:145] op_sel_hi:[1,0]
	s_waitcnt lgkmcnt(1)
	v_lshlrev_b32_e32 v44, 16, v32
	v_and_b32_e32 v32, 0xffff0000, v32
	v_mul_f32_e32 v7, v7, v32
	v_lshlrev_b32_e32 v32, 16, v33
	v_mul_f32_e32 v8, v8, v32
	v_and_b32_e32 v32, 0xffff0000, v33
	v_mul_f32_e32 v9, v9, v32
	s_waitcnt lgkmcnt(0)
	v_lshlrev_b32_e32 v32, 16, v34
	v_mul_f32_e32 v10, v10, v32
	v_and_b32_e32 v32, 0xffff0000, v34
	v_mul_f32_e32 v11, v11, v32
	v_lshlrev_b32_e32 v32, 16, v35
	v_mul_f32_e32 v12, v12, v32
	v_and_b32_e32 v32, 0xffff0000, v35
	v_mul_f32_e32 v6, v6, v44
	v_mul_f32_e32 v13, v13, v32
	v_cvt_pk_bf16_f32 v6, v6, v7
	v_cvt_pk_bf16_f32 v7, v8, v9
	v_cvt_pk_bf16_f32 v8, v10, v11
	v_cvt_pk_bf16_f32 v9, v12, v13
	ds_read_b128 v[10:13], v219
	ds_read_b128 v[32:35], v220
	ds_read_b64_tr_b16 v[44:45], v228 offset:18432
	ds_read_b64_tr_b16 v[46:47], v228 offset:19968
	v_pk_mul_f32 v[18:19], v[18:19], v[144:145] op_sel_hi:[1,0]
	v_pk_mul_f32 v[16:17], v[16:17], v[144:145] op_sel_hi:[1,0]
	s_mov_b32 s20, 0x800000
	s_waitcnt lgkmcnt(1)
	v_lshlrev_b32_e32 v53, 16, v44
	v_and_b32_e32 v44, 0xffff0000, v44
	v_mul_f32_e32 v11, v11, v44
	v_lshlrev_b32_e32 v44, 16, v45
	v_mul_f32_e32 v12, v12, v44
	v_and_b32_e32 v44, 0xffff0000, v45
	v_mul_f32_e32 v13, v13, v44
	s_waitcnt lgkmcnt(0)
	v_lshlrev_b32_e32 v44, 16, v46
	v_mul_f32_e32 v32, v32, v44
	v_and_b32_e32 v44, 0xffff0000, v46
	v_mul_f32_e32 v33, v33, v44
	v_lshlrev_b32_e32 v44, 16, v47
	v_mul_f32_e32 v34, v34, v44
	v_and_b32_e32 v44, 0xffff0000, v47
	v_mul_f32_e32 v10, v10, v53
	v_mul_f32_e32 v35, v35, v44
	v_cvt_pk_bf16_f32 v10, v10, v11
	v_cvt_pk_bf16_f32 v11, v12, v13
	v_cvt_pk_bf16_f32 v12, v32, v33
	v_cvt_pk_bf16_f32 v13, v34, v35
	ds_read_b128 v[32:35], v221
	ds_read_b128 v[44:47], v222
	ds_read_b64_tr_b16 v[54:55], v227 offset:27648
	ds_read_b64_tr_b16 v[56:57], v227 offset:29184
	v_mfma_f32_32x32x16_bf16 v[16:31], v[120:123], v[2:5], v[16:31]
	s_waitcnt lgkmcnt(1)
	v_lshlrev_b32_e32 v53, 16, v54
	v_mul_f32_e32 v32, v32, v53
	v_and_b32_e32 v53, 0xffff0000, v54
	v_mul_f32_e32 v33, v33, v53
	v_lshlrev_b32_e32 v53, 16, v55
	v_mul_f32_e32 v34, v34, v53
	v_and_b32_e32 v53, 0xffff0000, v55
	v_mul_f32_e32 v35, v35, v53
	s_waitcnt lgkmcnt(0)
	v_lshlrev_b32_e32 v53, 16, v56
	v_mul_f32_e32 v44, v44, v53
	v_and_b32_e32 v53, 0xffff0000, v56
	v_mul_f32_e32 v45, v45, v53
	v_lshlrev_b32_e32 v53, 16, v57
	v_mul_f32_e32 v46, v46, v53
	v_and_b32_e32 v53, 0xffff0000, v57
	v_mul_f32_e32 v47, v47, v53
	v_cvt_pk_bf16_f32 v32, v32, v33
	v_cvt_pk_bf16_f32 v33, v34, v35
	v_cvt_pk_bf16_f32 v34, v44, v45
	v_mov_b32_e32 v44, s33
	v_cvt_pk_bf16_f32 v35, v46, v47
	v_add_u32_e32 v53, s27, v210
	ds_read_b128 v[44:47], v44 offset:1024
	ds_read_u16 v54, v53 offset:9216
	ds_read_u16 v55, v53 offset:9360
	v_add_u32_e32 v56, s88, v210
	v_mfma_f32_32x32x16_bf16 v[16:31], v[108:111], v[6:9], v[16:31]
	s_waitcnt lgkmcnt(1)
	v_lshlrev_b32_e32 v54, 16, v54
	s_waitcnt lgkmcnt(0)
	v_lshlrev_b32_e32 v55, 16, v55
	v_mul_f32_e64 v44, v44, v54
	v_mul_f32_e64 v45, v45, v55
	v_add_f32_e32 v44, 0, v44
	v_add_f32_e32 v54, v44, v45
	ds_read_u16 v44, v56 offset:9216
	ds_read_u16 v45, v53 offset:9648
	v_mfma_f32_32x32x16_bf16 v[16:31], v[116:119], v[10:13], v[16:31]
	s_waitcnt lgkmcnt(1)
	v_lshlrev_b32_e32 v44, 16, v44
	s_waitcnt lgkmcnt(0)
	v_lshlrev_b32_e32 v45, 16, v45
	v_mul_f32_e64 v44, v46, v44
	v_mul_f32_e64 v45, v47, v45
	v_add_f32_e32 v44, v54, v44
	v_add_f32_e32 v57, v44, v45
	v_mov_b32_e32 v44, s26
	ds_read_b128 v[44:47], v44 offset:1024
	ds_read_u16 v54, v56 offset:9504
	ds_read_u16 v55, v53 offset:9936
	v_mfma_f32_32x32x16_bf16 v[16:31], v[112:115], v[32:35], v[16:31]
	s_waitcnt lgkmcnt(1)
	v_lshlrev_b32_e32 v54, 16, v54
	s_waitcnt lgkmcnt(0)
	v_lshlrev_b32_e32 v55, 16, v55
	v_mul_f32_e64 v44, v44, v54
	v_mul_f32_e64 v45, v45, v55
	v_add_f32_e32 v44, v57, v44
	v_add_f32_e32 v54, v44, v45
	ds_read_u16 v44, v56 offset:9792
	ds_read_u16 v45, v53 offset:10224
	s_waitcnt lgkmcnt(1)
	v_lshlrev_b32_e32 v44, 16, v44
	s_waitcnt lgkmcnt(0)
	v_lshlrev_b32_e32 v45, 16, v45
	v_pk_mul_f32 v[44:45], v[46:47], v[44:45]
	s_nop 0
	v_add_f32_e32 v44, v54, v44
	v_add_f32_e32 v44, v44, v45
	ds_write_b32 v185, v44
	s_waitcnt lgkmcnt(0)
	s_barrier
	ds_read_b32 v2, v209
	ds_read_b32 v3, v211
	s_waitcnt lgkmcnt(0)
	v_add_f32_e32 v2, v2, v3
	ds_read_b32 v3, v212
	s_waitcnt lgkmcnt(0)
	v_add_f32_e32 v2, v2, v3
	ds_read_b32 v3, v213
	s_waitcnt lgkmcnt(0)
	v_add_f32_e32 v2, v2, v3
	v_fmamk_f32 v2, v2, 0x3c000000, v192
	v_cmp_gt_f32_e32 vcc, s20, v2
	v_mul_f32_e32 v3, 0x4b800000, v2
	v_readlane_b32 s20, v251, 8
	v_cndmask_b32_e32 v2, v2, v3, vcc
	v_rsq_f32_e32 v2, v2
	v_readlane_b32 s21, v251, 9
	v_readlane_b32 s22, v251, 10
	v_readlane_b32 s23, v251, 11
	v_mul_f32_e32 v3, 0x45800000, v2
	v_cndmask_b32_e32 v8, v2, v3, vcc
	v_lshl_add_u64 v[6:7], s[20:21], 0, v[136:137]
	s_andn2_b64 vcc, exec, s[86:87]
	v_lshrrev_b32_e32 v4, 5, v194
	v_mul_u32_u24_e32 v4, 24, v4
	v_mov_b32_e32 v5, 0
	v_lshl_add_u64 v[6:7], v[6:7], 0, v[4:5]
	s_cmp_gt_u32 s89, 29
	s_cbranch_scc1 .Lhw_0
	s_cmp_lg_u64 s[72:73], 0
	s_cbranch_scc1 .Lhw_9
	s_waitcnt vmcnt(7)
	s_branch .Lhw_done
.Lhw_9:
	s_waitcnt vmcnt(9)
	s_branch .Lhw_done

; #define LAS __attribute__((address_space(3)))
; DI float lo_f(unsigned u) { return __uint_as_float(u << 16); }
; DI float hi_f(unsigned u) { return __uint_as_float(u & 0xffff0000u); }
; DI unsigned pk2(float lo, float hi) { return pg8::cvt_pk_bf16(lo, hi); }
; DI void mlstm_seq(LAS unsigned char* lds, const bf16* P, const float* IFg, bf16* Hout, const float* conv_w, const float* conv_b, const float* mlg, int seq) {
;     ...
; #pragma unroll
;         for (int rq = 0; rq < 4; ++rq) { const int dv = 32 * dvs + 8 * rq + 4 * hh; const f32x4 gl = *(const LAS f32x4*)(mlgl + dv);
;             const float o0 = hv[4 * rq] * rstd * gl[0] * lo_f(og[rq].x), o1 = hv[4 * rq + 1] * rstd * gl[1] * hi_f(og[rq].x), o2 = hv[4 * rq + 2] * rstd * gl[2] * lo_f(og[rq].y), o3 = hv[4 * rq + 3] * rstd * gl[3] * hi_f(og[rq].y);
;             v2u w; w.x = pk2(o0, o1); w.y = pk2(o2, o3); *(v2u*)(Hout + row * 1024 + hd * 128 + dv) = w;
;             v2u cw; cw.x = pk2(Cst[4 * rq], Cst[4 * rq + 1]); cw.y = pk2(Cst[4 * rq + 2], Cst[4 * rq + 3]);
;             *(LAS v2u*)(Cimg + (32 * th + r32) * 320 + 2 * dv) = cw; }
;         if (wv == 5) { float s = 0.f;
; #pragma unroll
;             for (int w = 0; w < 8; ++w) s += npart[w * 64 + lane];
;             n_reg = dec * n_reg + s; nvec[lane] = n_reg; }
.Lhw_done:
	ds_read_b128 v[2:5], v204
	v_mul_f32_e32 v0, v0, v8
	s_waitcnt lgkmcnt(0)
	v_mul_f32_e32 v0, v2, v0
	v_lshlrev_b32_e32 v2, 16, v152
	v_mul_f32_e32 v0, v0, v2
	v_mul_f32_e32 v2, v14, v8
	v_mul_f32_e32 v2, v3, v2
	v_and_b32_e32 v3, 0xffff0000, v152
	v_mul_f32_e32 v2, v2, v3
	v_mul_f32_e32 v3, v48, v8
	v_mul_f32_e32 v3, v4, v3
	v_lshlrev_b32_e32 v4, 16, v153
	v_mul_f32_e32 v3, v3, v4
	v_mul_f32_e32 v4, v49, v8
	v_mul_f32_e32 v4, v5, v4
	v_and_b32_e32 v5, 0xffff0000, v153
	v_mul_f32_e32 v4, v4, v5
	v_cvt_pk_bf16_f32 v152, v0, v2
	v_cvt_pk_bf16_f32 v153, v3, v4
	v_add_u32_e32 v0, v140, v208
	v_cvt_pk_bf16_f32 v2, v16, v17
	v_cvt_pk_bf16_f32 v3, v18, v19
	ds_write_b64 v0, v[2:3] offset:51200
	ds_read_b128 v[2:5], v206
	v_mul_f32_e32 v0, v40, v8
	s_waitcnt lgkmcnt(0)
	v_mul_f32_e32 v0, v2, v0
	v_lshlrev_b32_e32 v2, 16, v148
	v_mul_f32_e32 v0, v0, v2
	v_mul_f32_e32 v2, v41, v8
	v_mul_f32_e32 v2, v3, v2
	v_and_b32_e32 v3, 0xffff0000, v148
	v_mul_f32_e32 v2, v2, v3
	v_mul_f32_e32 v3, v42, v8
	v_mul_f32_e32 v3, v4, v3
	v_lshlrev_b32_e32 v4, 16, v149
	v_mul_f32_e32 v3, v3, v4
	v_mul_f32_e32 v4, v43, v8
	v_mul_f32_e32 v4, v5, v4
	v_and_b32_e32 v5, 0xffff0000, v149
	v_mul_f32_e32 v4, v4, v5
	v_cvt_pk_bf16_f32 v42, v0, v2
	v_cvt_pk_bf16_f32 v43, v3, v4
	v_mov_b32_e32 v40, v152
	v_mov_b32_e32 v41, v153
	v_cvt_pk_bf16_f32 v2, v20, v21
	v_cvt_pk_bf16_f32 v3, v22, v23
	ds_write_b64 v229, v[2:3] offset:51200
	ds_read_b128 v[2:5], v207
	v_mul_f32_e32 v0, v36, v8
	s_waitcnt lgkmcnt(0)
	v_mul_f32_e32 v0, v2, v0
	v_lshlrev_b32_e32 v2, 16, v146
	v_mul_f32_e32 v0, v0, v2
	v_mul_f32_e32 v2, v37, v8
	v_mul_f32_e32 v2, v3, v2
	v_and_b32_e32 v3, 0xffff0000, v146
	v_mul_f32_e32 v2, v2, v3
	v_mul_f32_e32 v3, v38, v8
	v_mul_f32_e32 v3, v4, v3
	v_lshlrev_b32_e32 v4, 16, v147
	v_mul_f32_e32 v3, v3, v4
	v_mul_f32_e32 v4, v39, v8
	v_mul_f32_e32 v4, v5, v4
	v_and_b32_e32 v5, 0xffff0000, v147
	v_mul_f32_e32 v4, v4, v5
	v_cvt_pk_bf16_f32 v38, v0, v2
	v_cvt_pk_bf16_f32 v39, v3, v4
	v_cvt_pk_bf16_f32 v2, v24, v25
	v_cvt_pk_bf16_f32 v3, v26, v27
	ds_write_b64 v230, v[2:3] offset:51200
	ds_read_b128 v[2:5], v205
	v_mul_f32_e32 v0, v15, v8
	s_waitcnt lgkmcnt(0)
	v_mul_f32_e32 v0, v2, v0
	v_lshlrev_b32_e32 v2, 16, v150
	v_mul_f32_e32 v0, v0, v2
	v_mul_f32_e32 v2, v50, v8
	v_mul_f32_e32 v2, v3, v2
	v_and_b32_e32 v3, 0xffff0000, v150
	v_mul_f32_e32 v2, v2, v3
	v_mul_f32_e32 v3, v51, v8
	v_mul_f32_e32 v3, v4, v3
	v_lshlrev_b32_e32 v4, 16, v151
	v_mul_f32_e32 v3, v3, v4
	v_mul_f32_e32 v4, v52, v8
	v_mul_f32_e32 v4, v5, v4
	v_and_b32_e32 v5, 0xffff0000, v151
	v_mul_f32_e32 v4, v4, v5
	v_cvt_pk_bf16_f32 v36, v0, v2
	v_cvt_pk_bf16_f32 v37, v3, v4
	v_cvt_pk_bf16_f32 v2, v28, v29
	v_cvt_pk_bf16_f32 v3, v30, v31
	ds_write_b64 v231, v[2:3] offset:51200
	s_nop 1
	v_permlane32_swap_b32_e32 v40, v42
	v_permlane32_swap_b32_e32 v41, v43
	v_permlane32_swap_b32_e32 v36, v38
	v_permlane32_swap_b32_e32 v37, v39
	global_store_dwordx4 v[6:7], v[40:43], off offset:-32
	global_store_dwordx4 v[6:7], v[36:39], off offset:-16
	s_cbranch_vccnz .LBB0_385
	ds_read2st64_b32 v[2:3], v184 offset1:1
	s_waitcnt lgkmcnt(0)
	v_add_f32_e32 v0, 0, v2
	v_add_f32_e32 v0, v0, v3
	ds_read2st64_b32 v[2:3], v184 offset0:2 offset1:3
	s_waitcnt lgkmcnt(0)
	v_add_f32_e32 v0, v0, v2
	v_add_f32_e32 v0, v0, v3
	ds_read2st64_b32 v[2:3], v184 offset0:4 offset1:5
	s_waitcnt lgkmcnt(0)
	v_add_f32_e32 v0, v0, v2
	v_add_f32_e32 v0, v0, v3
	ds_read2st64_b32 v[2:3], v184 offset0:6 offset1:7
	s_waitcnt lgkmcnt(0)
	v_add_f32_e32 v0, v0, v2
	v_add_f32_e32 v0, v0, v3
	v_fmac_f32_e32 v0, v223, v144
	v_mov_b32_e32 v223, v0
	ds_write_b32 v186, v0
